# Down-proj split-K: 11-way split of leftover tiles for f=1..3 (was 5-way)
# speedup vs baseline: 1.0064x; 1.0064x over previous
.LBB0_1274:
	s_add_u32 s37, s22, 0xb738000
	s_addc_u32 s46, s23, 0
	s_add_i32 m0, s66, 0x18000
	v_lshl_add_u64 v[8:9], v[8:9], 0, s[40:41]
	s_waitcnt vmcnt(4)
	s_barrier
	global_load_lds_dwordx4 v[8:9], off
	v_lshl_add_u64 v[6:7], v[6:7], 0, s[40:41]
	s_add_i32 m0, s66, 0x1a000
	s_add_i32 s71, s66, 0x8000
	global_load_lds_dwordx4 v[6:7], off
	v_lshl_add_u64 v[4:5], v[4:5], 0, s[40:41]
	s_mov_b32 m0, s71
	s_add_i32 s72, s66, 0xa000
	global_load_lds_dwordx4 v[4:5], off
	v_lshl_add_u64 v[2:3], v[2:3], 0, s[40:41]
	s_mov_b32 m0, s72
	v_lshl_add_u64 v[0:1], v[0:1], 0, s[40:41]
	global_load_lds_dwordx4 v[2:3], off
	s_add_i32 m0, s66, 0x1c000
	v_bfe_u32 v193, v231, 4, 2
	global_load_lds_dwordx4 v[0:1], off
	v_lshl_add_u64 v[0:1], v[10:11], 0, s[40:41]
	s_add_i32 m0, s66, 0x1e000
	v_and_b32_e32 v192, 15, v231
	global_load_lds_dwordx4 v[0:1], off
	v_lshlrev_b32_e32 v0, 4, v193
	v_lshlrev_b32_e32 v194, 2, v231
	s_lshr_b32 s79, s27, 6
	s_and_b32 s27, s2, 3
	v_lshl_or_b32 v0, v192, 6, v0
	s_lshl_b32 s2, s3, 13
	v_and_b32_e32 v1, 32, v194
	s_lshl_b32 s70, s3, 6
	v_bitop3_b32 v2, v0, s2, v1 bitop3:0xde
	s_lshl_b32 s73, s27, 5
	s_lshl_b32 s2, s27, 12
	v_bitop3_b32 v195, s2, v0, v1 bitop3:0xf6
	s_movk_i32 s98, 0xdc
	s_mov_b32 s99, 0x2e8ba2e9
	s_cmp_eq_u32 s43, 2
	s_cbranch_scc0 .Ldsp_s1
	s_movk_i32 s98, 0x64
	s_mov_b32 s99, 0x66666667
.Ldsp_s1:
	s_cmp_lt_i32 s14, s98
	s_mul_hi_i32 s2, s14, s99
	s_cselect_b64 s[62:63], -1, 0
	s_lshr_b32 s3, s2, 31
	s_ashr_i32 s2, s2, 1
	s_add_i32 s2, s2, s3
	s_add_i32 s3, s2, 0x100
	s_ashr_i32 s6, s3, 31
	s_lshr_b32 s6, s6, 29
	s_add_i32 s6, s3, s6
	s_ashr_i32 s7, s6, 3
	s_and_b32 s6, s6, -8
	s_cmp_eq_u32 s43, 2
	s_cselect_b32 s98, 5, 11
	s_mul_i32 s2, s2, s98
	s_sub_i32 s3, s3, s6
	s_sub_i32 s2, s14, s2
	s_mul_i32 s6, s3, 34
	s_mul_i32 s11, s2, 10
	s_add_i32 s6, s6, 4
	s_add_i32 s20, s11, -6
	s_lshl_b32 s21, s2, 3
	s_cmp_lt_i32 s3, 4
	s_mul_i32 s3, s3, 35
	s_cselect_b32 s3, s3, s6
	s_add_i32 s3, s3, s7
	s_ashr_i32 s6, s3, 31
	s_lshr_b32 s6, s6, 28
	s_add_i32 s6, s3, s6
	s_ashr_i32 s7, s6, 4
	s_lshl_b32 s24, s7, 2
	s_sub_i32 s7, 0x45, s24
	s_min_u32 s28, s7, 4
	s_and_b32 s6, s6, -16
	s_sub_i32 s29, s3, s6
	v_cvt_f32_ubyte0_e32 v1, s28
	v_cvt_f32_i32_e32 v0, s29
	v_rcp_iflag_f32_e32 v3, v1
	s_cmp_lt_i32 s2, 3
	s_cselect_b32 s20, s21, s20
	s_cselect_b32 s74, 8, 10
	s_cmp_eq_u32 s43, 2
	s_cbranch_scc1 .Ldsp_keep5
	s_lshl_b32 s20, s2, 2
	s_mov_b32 s74, 4
.Ldsp_keep5:
	v_mul_f32_e32 v3, v0, v3
	v_trunc_f32_e32 v3, v3
	v_fma_f32 v0, -v3, v1, v0
	v_cvt_i32_f32_e32 v3, v3
	s_ashr_i32 s2, s29, 30
	s_or_b32 s21, s2, 1
	v_cmp_ge_f32_e64 s[2:3], |v0|, v1
	s_and_b64 s[2:3], s[2:3], exec
	s_cselect_b32 s2, s21, 0
	v_readfirstlane_b32 s3, v3
	s_add_i32 s2, s3, s2
	v_add_u32_e32 v0, v14, v12
	s_sext_i32_i8 s75, s2
	s_mul_i32 s2, s2, s28
	v_add_lshl_u32 v0, v0, v13, 1
	v_mov_b32_e32 v1, v177
	s_waitcnt vmcnt(6)
	s_sub_i32 s2, s29, s2
	v_lshl_add_u64 v[158:159], s[4:5], 0, v[0:1]
	v_add_u32_e32 v0, v17, v15
	s_sext_i32_i8 s2, s2
	v_add_lshl_u32 v0, v0, v16, 1
	s_mov_b32 s11, s10
	s_mov_b32 s6, s10
	s_mov_b32 s7, s10
	s_add_i32 s76, s24, s2
	v_lshl_add_u64 v[160:161], s[4:5], 0, v[0:1]
	s_mov_b32 s24, -1
	v_add_u32_e32 v196, 0, v2
	s_barrier
	s_branch .LBB0_1277

.LBB0_1416:
	s_add_i32 s3, s6, s2
	s_ashr_i32 s2, s3, 31
	s_lshr_b32 s2, s2, 28
	s_add_i32 s5, s3, s2
	s_ashr_i32 s2, s5, 4
	s_lshl_b32 s2, s2, 2
	s_sub_i32 s6, 0x45, s2
	s_min_u32 s11, s6, 4
	s_and_b32 s5, s5, -16
	s_sub_i32 s5, s3, s5
	v_cvt_f32_ubyte0_e32 v1, s11
	v_cvt_f32_i32_e32 v0, s5
	v_rcp_iflag_f32_e32 v2, v1
	s_ashr_i32 s3, s5, 30
	s_or_b32 s3, s3, 1
	v_mov_b32_e32 v4, v231
	v_mul_f32_e32 v2, v0, v2
	v_trunc_f32_e32 v2, v2
	v_fma_f32 v0, -v2, v1, v0
	v_cvt_i32_f32_e32 v2, v2
	v_cmp_ge_f32_e64 s[6:7], |v0|, v1
	s_and_b64 s[6:7], s[6:7], exec
	s_cselect_b32 s3, s3, 0
	v_readfirstlane_b32 s6, v2
	s_add_i32 s3, s6, s3
	s_mul_i32 s6, s3, s11
	s_sub_i32 s5, s5, s6
	s_cmp_eq_u32 s43, 2
	s_cselect_b32 s98, 5, 11
	s_mul_i32 s6, s4, s98
	s_ashr_i32 s7, s6, 31
	s_lshl_b64 s[6:7], s[6:7], 17
	s_add_u32 s6, s37, s6
	s_addc_u32 s7, s46, s7
	v_ashrrev_i32_e32 v5, 31, v4
	v_lshl_add_u64 v[0:1], v[4:5], 4, s[6:7]
	s_bfe_u32 s6, s14, 0x10002
	s_and_b32 s7, s14, 3
	s_lshl_b32 s4, s7, 13
	s_lshl_b32 s11, s6, 16
	s_or_b32 s24, s11, s4
	v_lshl_add_u64 v[28:29], v[0:1], 0, s[24:25]
	v_mov_b32_e32 v100, 0
	v_mov_b32_e32 v101, 0
	v_mov_b32_e32 v102, 0
	v_mov_b32_e32 v103, 0
	v_mov_b32_e32 v104, 0
	v_mov_b32_e32 v105, 0
	v_mov_b32_e32 v106, 0
	v_mov_b32_e32 v107, 0
	v_mov_b32_e32 v108, 0
	v_mov_b32_e32 v109, 0
	v_mov_b32_e32 v110, 0
	v_mov_b32_e32 v111, 0
	v_mov_b32_e32 v112, 0
	v_mov_b32_e32 v113, 0
	v_mov_b32_e32 v114, 0
	v_mov_b32_e32 v115, 0
	s_cmp_eq_u32 s43, 2
	s_cbranch_scc1 .Ldsp_fx_skip
	s_mov_b32 s99, 0
	s_mov_b32 s98, 0xa0000
	v_lshl_add_u64 v[116:117], v[28:29], 0, s[98:99]
	global_load_dwordx4 v[120:123], v[116:117], off
	s_mov_b32 s98, 0xa8000
	v_lshl_add_u64 v[116:117], v[28:29], 0, s[98:99]
	global_load_dwordx4 v[124:127], v[116:117], off
	s_mov_b32 s98, 0xc0000
	v_lshl_add_u64 v[116:117], v[28:29], 0, s[98:99]
	global_load_dwordx4 v[128:131], v[116:117], off
	s_mov_b32 s98, 0xc8000
	v_lshl_add_u64 v[116:117], v[28:29], 0, s[98:99]
	global_load_dwordx4 v[132:135], v[116:117], off
	s_mov_b32 s98, 0xe0000
	v_lshl_add_u64 v[116:117], v[28:29], 0, s[98:99]
	global_load_dwordx4 v[136:139], v[116:117], off
	s_mov_b32 s98, 0xe8000
	v_lshl_add_u64 v[116:117], v[28:29], 0, s[98:99]
	global_load_dwordx4 v[140:143], v[116:117], off
	s_mov_b32 s98, 0x100000
	v_lshl_add_u64 v[116:117], v[28:29], 0, s[98:99]
	global_load_dwordx4 v[144:147], v[116:117], off
	s_mov_b32 s98, 0x108000
	v_lshl_add_u64 v[116:117], v[28:29], 0, s[98:99]
	global_load_dwordx4 v[148:151], v[116:117], off
	s_mov_b32 s98, 0x120000
	v_lshl_add_u64 v[116:117], v[28:29], 0, s[98:99]
	global_load_dwordx4 v[152:155], v[116:117], off
	s_mov_b32 s98, 0x128000
	v_lshl_add_u64 v[116:117], v[28:29], 0, s[98:99]
	global_load_dwordx4 v[156:159], v[116:117], off
	s_mov_b32 s98, 0x140000
	v_lshl_add_u64 v[116:117], v[28:29], 0, s[98:99]
	global_load_dwordx4 v[160:163], v[116:117], off
	s_mov_b32 s98, 0x148000
	v_lshl_add_u64 v[116:117], v[28:29], 0, s[98:99]
	global_load_dwordx4 v[164:167], v[116:117], off
	s_waitcnt vmcnt(0)
	v_lshlrev_b32_e32 v118, 16, v120
	v_and_b32_e32 v119, 0xffff0000, v120
	v_add_f32_e32 v100, v100, v118
	v_add_f32_e32 v101, v101, v119
	v_lshlrev_b32_e32 v118, 16, v121
	v_and_b32_e32 v119, 0xffff0000, v121
	v_add_f32_e32 v102, v102, v118
	v_add_f32_e32 v103, v103, v119
	v_lshlrev_b32_e32 v118, 16, v122
	v_and_b32_e32 v119, 0xffff0000, v122
	v_add_f32_e32 v104, v104, v118
	v_add_f32_e32 v105, v105, v119
	v_lshlrev_b32_e32 v118, 16, v123
	v_and_b32_e32 v119, 0xffff0000, v123
	v_add_f32_e32 v106, v106, v118
	v_add_f32_e32 v107, v107, v119
	v_lshlrev_b32_e32 v118, 16, v124
	v_and_b32_e32 v119, 0xffff0000, v124
	v_add_f32_e32 v108, v108, v118
	v_add_f32_e32 v109, v109, v119
	v_lshlrev_b32_e32 v118, 16, v125
	v_and_b32_e32 v119, 0xffff0000, v125
	v_add_f32_e32 v110, v110, v118
	v_add_f32_e32 v111, v111, v119
	v_lshlrev_b32_e32 v118, 16, v126
	v_and_b32_e32 v119, 0xffff0000, v126
	v_add_f32_e32 v112, v112, v118
	v_add_f32_e32 v113, v113, v119
	v_lshlrev_b32_e32 v118, 16, v127
	v_and_b32_e32 v119, 0xffff0000, v127
	v_add_f32_e32 v114, v114, v118
	v_add_f32_e32 v115, v115, v119
	v_lshlrev_b32_e32 v118, 16, v128
	v_and_b32_e32 v119, 0xffff0000, v128
	v_add_f32_e32 v100, v100, v118
	v_add_f32_e32 v101, v101, v119
	v_lshlrev_b32_e32 v118, 16, v129
	v_and_b32_e32 v119, 0xffff0000, v129
	v_add_f32_e32 v102, v102, v118
	v_add_f32_e32 v103, v103, v119
	v_lshlrev_b32_e32 v118, 16, v130
	v_and_b32_e32 v119, 0xffff0000, v130
	v_add_f32_e32 v104, v104, v118
	v_add_f32_e32 v105, v105, v119
	v_lshlrev_b32_e32 v118, 16, v131
	v_and_b32_e32 v119, 0xffff0000, v131
	v_add_f32_e32 v106, v106, v118
	v_add_f32_e32 v107, v107, v119
	v_lshlrev_b32_e32 v118, 16, v132
	v_and_b32_e32 v119, 0xffff0000, v132
	v_add_f32_e32 v108, v108, v118
	v_add_f32_e32 v109, v109, v119
	v_lshlrev_b32_e32 v118, 16, v133
	v_and_b32_e32 v119, 0xffff0000, v133
	v_add_f32_e32 v110, v110, v118
	v_add_f32_e32 v111, v111, v119
	v_lshlrev_b32_e32 v118, 16, v134
	v_and_b32_e32 v119, 0xffff0000, v134
	v_add_f32_e32 v112, v112, v118
	v_add_f32_e32 v113, v113, v119
	v_lshlrev_b32_e32 v118, 16, v135
	v_and_b32_e32 v119, 0xffff0000, v135
	v_add_f32_e32 v114, v114, v118
	v_add_f32_e32 v115, v115, v119
	v_lshlrev_b32_e32 v118, 16, v136
	v_and_b32_e32 v119, 0xffff0000, v136
	v_add_f32_e32 v100, v100, v118
	v_add_f32_e32 v101, v101, v119
	v_lshlrev_b32_e32 v118, 16, v137
	v_and_b32_e32 v119, 0xffff0000, v137
	v_add_f32_e32 v102, v102, v118
	v_add_f32_e32 v103, v103, v119
	v_lshlrev_b32_e32 v118, 16, v138
	v_and_b32_e32 v119, 0xffff0000, v138
	v_add_f32_e32 v104, v104, v118
	v_add_f32_e32 v105, v105, v119
	v_lshlrev_b32_e32 v118, 16, v139
	v_and_b32_e32 v119, 0xffff0000, v139
	v_add_f32_e32 v106, v106, v118
	v_add_f32_e32 v107, v107, v119
	v_lshlrev_b32_e32 v118, 16, v140
	v_and_b32_e32 v119, 0xffff0000, v140
	v_add_f32_e32 v108, v108, v118
	v_add_f32_e32 v109, v109, v119
	v_lshlrev_b32_e32 v118, 16, v141
	v_and_b32_e32 v119, 0xffff0000, v141
	v_add_f32_e32 v110, v110, v118
	v_add_f32_e32 v111, v111, v119
	v_lshlrev_b32_e32 v118, 16, v142
	v_and_b32_e32 v119, 0xffff0000, v142
	v_add_f32_e32 v112, v112, v118
	v_add_f32_e32 v113, v113, v119
	v_lshlrev_b32_e32 v118, 16, v143
	v_and_b32_e32 v119, 0xffff0000, v143
	v_add_f32_e32 v114, v114, v118
	v_add_f32_e32 v115, v115, v119
	v_lshlrev_b32_e32 v118, 16, v144
	v_and_b32_e32 v119, 0xffff0000, v144
	v_add_f32_e32 v100, v100, v118
	v_add_f32_e32 v101, v101, v119
	v_lshlrev_b32_e32 v118, 16, v145
	v_and_b32_e32 v119, 0xffff0000, v145
	v_add_f32_e32 v102, v102, v118
	v_add_f32_e32 v103, v103, v119
	v_lshlrev_b32_e32 v118, 16, v146
	v_and_b32_e32 v119, 0xffff0000, v146
	v_add_f32_e32 v104, v104, v118
	v_add_f32_e32 v105, v105, v119
	v_lshlrev_b32_e32 v118, 16, v147
	v_and_b32_e32 v119, 0xffff0000, v147
	v_add_f32_e32 v106, v106, v118
	v_add_f32_e32 v107, v107, v119
	v_lshlrev_b32_e32 v118, 16, v148
	v_and_b32_e32 v119, 0xffff0000, v148
	v_add_f32_e32 v108, v108, v118
	v_add_f32_e32 v109, v109, v119
	v_lshlrev_b32_e32 v118, 16, v149
	v_and_b32_e32 v119, 0xffff0000, v149
	v_add_f32_e32 v110, v110, v118
	v_add_f32_e32 v111, v111, v119
	v_lshlrev_b32_e32 v118, 16, v150
	v_and_b32_e32 v119, 0xffff0000, v150
	v_add_f32_e32 v112, v112, v118
	v_add_f32_e32 v113, v113, v119
	v_lshlrev_b32_e32 v118, 16, v151
	v_and_b32_e32 v119, 0xffff0000, v151
	v_add_f32_e32 v114, v114, v118
	v_add_f32_e32 v115, v115, v119
	v_lshlrev_b32_e32 v118, 16, v152
	v_and_b32_e32 v119, 0xffff0000, v152
	v_add_f32_e32 v100, v100, v118
	v_add_f32_e32 v101, v101, v119
	v_lshlrev_b32_e32 v118, 16, v153
	v_and_b32_e32 v119, 0xffff0000, v153
	v_add_f32_e32 v102, v102, v118
	v_add_f32_e32 v103, v103, v119
	v_lshlrev_b32_e32 v118, 16, v154
	v_and_b32_e32 v119, 0xffff0000, v154
	v_add_f32_e32 v104, v104, v118
	v_add_f32_e32 v105, v105, v119
	v_lshlrev_b32_e32 v118, 16, v155
	v_and_b32_e32 v119, 0xffff0000, v155
	v_add_f32_e32 v106, v106, v118
	v_add_f32_e32 v107, v107, v119
	v_lshlrev_b32_e32 v118, 16, v156
	v_and_b32_e32 v119, 0xffff0000, v156
	v_add_f32_e32 v108, v108, v118
	v_add_f32_e32 v109, v109, v119
	v_lshlrev_b32_e32 v118, 16, v157
	v_and_b32_e32 v119, 0xffff0000, v157
	v_add_f32_e32 v110, v110, v118
	v_add_f32_e32 v111, v111, v119
	v_lshlrev_b32_e32 v118, 16, v158
	v_and_b32_e32 v119, 0xffff0000, v158
	v_add_f32_e32 v112, v112, v118
	v_add_f32_e32 v113, v113, v119
	v_lshlrev_b32_e32 v118, 16, v159
	v_and_b32_e32 v119, 0xffff0000, v159
	v_add_f32_e32 v114, v114, v118
	v_add_f32_e32 v115, v115, v119
	v_lshlrev_b32_e32 v118, 16, v160
	v_and_b32_e32 v119, 0xffff0000, v160
	v_add_f32_e32 v100, v100, v118
	v_add_f32_e32 v101, v101, v119
	v_lshlrev_b32_e32 v118, 16, v161
	v_and_b32_e32 v119, 0xffff0000, v161
	v_add_f32_e32 v102, v102, v118
	v_add_f32_e32 v103, v103, v119
	v_lshlrev_b32_e32 v118, 16, v162
	v_and_b32_e32 v119, 0xffff0000, v162
	v_add_f32_e32 v104, v104, v118
	v_add_f32_e32 v105, v105, v119
	v_lshlrev_b32_e32 v118, 16, v163
	v_and_b32_e32 v119, 0xffff0000, v163
	v_add_f32_e32 v106, v106, v118
	v_add_f32_e32 v107, v107, v119
	v_lshlrev_b32_e32 v118, 16, v164
	v_and_b32_e32 v119, 0xffff0000, v164
	v_add_f32_e32 v108, v108, v118
	v_add_f32_e32 v109, v109, v119
	v_lshlrev_b32_e32 v118, 16, v165
	v_and_b32_e32 v119, 0xffff0000, v165
	v_add_f32_e32 v110, v110, v118
	v_add_f32_e32 v111, v111, v119
	v_lshlrev_b32_e32 v118, 16, v166
	v_and_b32_e32 v119, 0xffff0000, v166
	v_add_f32_e32 v112, v112, v118
	v_add_f32_e32 v113, v113, v119
	v_lshlrev_b32_e32 v118, 16, v167
	v_and_b32_e32 v119, 0xffff0000, v167
	v_add_f32_e32 v114, v114, v118
	v_add_f32_e32 v115, v115, v119
.Ldsp_fx_skip:
	s_mov_b32 s4, 0x20000
	v_add_co_u32_e32 v0, vcc, s4, v28
	global_load_dwordx4 v[12:15], v[28:29], off
	s_nop 0
	v_addc_co_u32_e32 v1, vcc, 0, v29, vcc
	global_load_dwordx4 v[20:23], v[0:1], off
	s_mov_b32 s4, 0x40000
	v_add_co_u32_e32 v0, vcc, s4, v28
	s_mov_b32 s4, 0x60000
	s_nop 0
	v_addc_co_u32_e32 v1, vcc, 0, v29, vcc
	global_load_dwordx4 v[0:3], v[0:1], off
	v_add_co_u32_e32 v6, vcc, s4, v28
	s_sext_i32_i8 s4, s3
	s_sext_i32_i8 s3, s5
	s_lshl_b32 s5, s6, 7
	s_lshl_b32 s6, s7, 4
	s_mov_b32 s11, 0x80000
	v_addc_co_u32_e32 v7, vcc, 0, v29, vcc
	s_or_b32 s5, s5, s6
	v_bfe_u32 v34, v4, 6, 2
	v_bfe_u32 v35, v4, 4, 2
	v_ashrrev_i32_e32 v5, 2, v4
	v_and_or_b32 v19, v4, 15, s5
	v_add_co_u32_e32 v4, vcc, s11, v28
	global_load_dwordx4 v[8:11], v[6:7], off
	v_and_b32_e32 v16, 0xffffffc0, v5
	v_addc_co_u32_e32 v5, vcc, 0, v29, vcc
	global_load_dwordx4 v[4:7], v[4:5], off
	s_add_i32 s2, s2, s3
	s_lshl_b32 s2, s2, 8
	v_lshlrev_b32_e32 v17, 5, v34
	v_lshlrev_b32_e32 v18, 3, v35
	s_lshl_b32 s3, s4, 8
	v_or3_b32 v18, v17, s3, v18
	s_waitcnt vmcnt(4)
	v_lshlrev_b32_e32 v27, 16, v15
	v_and_b32_e32 v15, 0xffff0000, v15
	v_lshlrev_b32_e32 v24, 16, v12
	v_and_b32_e32 v12, 0xffff0000, v12
	v_add_f32_e32 v30, 0, v15
	s_waitcnt vmcnt(3)
	v_and_b32_e32 v39, 0xffff0000, v23
	v_add_f32_e32 v12, 0, v12
	v_and_b32_e32 v31, 0xffff0000, v20
	v_add_f32_e32 v39, v30, v39
	v_add3_u32 v30, v19, v16, s2
	v_lshlrev_b32_e32 v32, 16, v21
	v_and_b32_e32 v33, 0xffff0000, v21
	v_add_f32_e32 v21, v12, v31
	v_ashrrev_i32_e32 v31, 31, v30
	v_lshlrev_b32_e32 v25, 16, v13
	v_and_b32_e32 v13, 0xffff0000, v13
	v_lshlrev_b64 v[16:17], 11, v[30:31]
	v_lshlrev_b32_e32 v26, 16, v14
	v_add_f32_e32 v25, 0, v25
	v_add_f32_e32 v13, 0, v13
	v_lshl_add_u64 v[16:17], s[12:13], 0, v[16:17]
	v_ashrrev_i32_e32 v19, 31, v18
	v_and_b32_e32 v14, 0xffff0000, v14
	v_add_f32_e32 v24, 0, v24
	v_add_f32_e32 v26, 0, v26
	v_add_f32_e32 v27, 0, v27
	v_lshlrev_b32_e32 v15, 16, v20
	v_lshlrev_b32_e32 v36, 16, v22
	v_and_b32_e32 v37, 0xffff0000, v22
	v_lshlrev_b32_e32 v38, 16, v23
	v_add_f32_e32 v22, v25, v32
	v_add_f32_e32 v23, v13, v33
	v_add_co_u32_e32 v12, vcc, s92, v28
	v_lshl_add_u64 v[32:33], v[18:19], 1, v[16:17]
	v_add_f32_e32 v14, 0, v14
	v_add_f32_e32 v20, v24, v15
	v_add_f32_e32 v36, v26, v36
	v_addc_co_u32_e32 v13, vcc, 0, v29, vcc
	v_add_f32_e32 v38, v27, v38
	global_load_dwordx4 v[24:27], v[32:33], off
	v_add_f32_e32 v37, v14, v37
	global_load_dwordx4 v[12:15], v[12:13], off
	s_waitcnt vmcnt(4)
	v_lshlrev_b32_e32 v40, 16, v0
	v_and_b32_e32 v0, 0xffff0000, v0
	s_mov_b32 s2, 0x28000
	v_lshlrev_b32_e32 v16, 16, v1
	v_and_b32_e32 v1, 0xffff0000, v1
	v_add_f32_e32 v19, v20, v40
	v_add_f32_e32 v40, v21, v0
	v_add_co_u32_e32 v0, vcc, s2, v28
	v_add_f32_e32 v41, v23, v1
	s_nop 0
	v_addc_co_u32_e32 v1, vcc, 0, v29, vcc
	s_mov_b32 s2, 0x48000
	v_lshlrev_b32_e32 v17, 16, v2
	v_and_b32_e32 v2, 0xffff0000, v2
	v_lshlrev_b32_e32 v18, 16, v3
	v_and_b32_e32 v3, 0xffff0000, v3
	v_add_f32_e32 v16, v22, v16
	global_load_dwordx4 v[20:23], v[0:1], off
	v_add_co_u32_e32 v0, vcc, s2, v28
	v_add_f32_e32 v17, v36, v17
	v_add_f32_e32 v2, v37, v2
	v_add_f32_e32 v18, v38, v18
	v_add_f32_e32 v3, v39, v3
	s_waitcnt vmcnt(4)
	v_lshlrev_b32_e32 v36, 16, v8
	v_lshlrev_b32_e32 v37, 16, v9
	v_lshlrev_b32_e32 v38, 16, v10
	v_lshlrev_b32_e32 v39, 16, v11
	v_addc_co_u32_e32 v1, vcc, 0, v29, vcc
	v_and_b32_e32 v9, 0xffff0000, v9
	v_add_f32_e32 v36, v19, v36
	v_add_f32_e32 v37, v16, v37
	v_add_f32_e32 v38, v17, v38
	v_add_f32_e32 v39, v18, v39
	global_load_dwordx4 v[16:19], v[0:1], off
	s_waitcnt vmcnt(4)
	v_lshlrev_b32_e32 v0, 16, v5
	s_mov_b32 s2, 0x68000
	v_and_b32_e32 v8, 0xffff0000, v8
	v_and_b32_e32 v10, 0xffff0000, v10
	v_add_f32_e32 v9, v41, v9
	v_and_b32_e32 v1, 0xffff0000, v5
	v_add_f32_e32 v37, v37, v0
	v_add_co_u32_e32 v0, vcc, s2, v28
	v_and_b32_e32 v11, 0xffff0000, v11
	v_add_f32_e32 v8, v40, v8
	v_add_f32_e32 v2, v2, v10
	v_lshlrev_b32_e32 v10, 16, v4
	v_and_b32_e32 v4, 0xffff0000, v4
	v_add_f32_e32 v42, v9, v1
	v_addc_co_u32_e32 v1, vcc, 0, v29, vcc
	s_mov_b32 s2, 0x88000
	v_add_f32_e32 v3, v3, v11
	v_add_f32_e32 v36, v36, v10
	v_add_f32_e32 v41, v8, v4
	global_load_dwordx4 v[8:11], v[0:1], off
	v_add_co_u32_e32 v0, vcc, s2, v28
	v_lshlrev_b32_e32 v5, 16, v6
	v_and_b32_e32 v6, 0xffff0000, v6
	v_lshlrev_b32_e32 v40, 16, v7
	v_and_b32_e32 v7, 0xffff0000, v7
	v_addc_co_u32_e32 v1, vcc, 0, v29, vcc
	v_add_f32_e32 v38, v38, v5
	v_add_f32_e32 v2, v2, v6
	v_add_f32_e32 v3, v3, v7
	global_load_dwordx4 v[4:7], v[0:1], off
	v_add_f32_e32 v39, v39, v40
	v_cmp_eq_u32_e32 vcc, 0, v35
	s_waitcnt vmcnt(5)
	v_lshlrev_b32_e32 v48, 16, v24
	v_and_b32_e32 v24, 0xffff0000, v24
	v_lshlrev_b32_e32 v49, 16, v25
	v_and_b32_e32 v25, 0xffff0000, v25
	v_lshlrev_b32_e32 v50, 16, v26
	v_and_b32_e32 v26, 0xffff0000, v26
	v_lshlrev_b32_e32 v51, 16, v27
	v_and_b32_e32 v27, 0xffff0000, v27
	s_waitcnt vmcnt(4)
	v_lshlrev_b32_e32 v40, 16, v12
	v_and_b32_e32 v43, 0xffff0000, v12
	v_lshlrev_b32_e32 v44, 16, v13
	v_and_b32_e32 v45, 0xffff0000, v13
	v_lshlrev_b32_e32 v46, 16, v14
	v_and_b32_e32 v47, 0xffff0000, v14
	v_lshlrev_b32_e32 v28, 16, v15
	v_and_b32_e32 v29, 0xffff0000, v15
	v_add_f32_e32 v36, v36, v100
	v_fmac_f32_e32 v48, s10, v36
	v_add_f32_e32 v38, v38, v104
	v_fmac_f32_e32 v50, s10, v38
	v_add_f32_e32 v41, v41, v101
	v_fmac_f32_e32 v24, s10, v41
	v_add_f32_e32 v2, v2, v105
	v_fmac_f32_e32 v26, s10, v2
	v_add_f32_e32 v37, v37, v102
	v_fmac_f32_e32 v49, s10, v37
	v_add_f32_e32 v39, v39, v106
	v_fmac_f32_e32 v51, s10, v39
	v_add_f32_e32 v42, v42, v103
	v_fmac_f32_e32 v25, s10, v42
	v_add_f32_e32 v3, v3, v107
	v_fmac_f32_e32 v27, s10, v3
	v_cvt_pk_bf16_f32 v0, v48, v24
	v_cvt_pk_bf16_f32 v1, v49, v25
	v_cvt_pk_bf16_f32 v2, v50, v26
	v_cvt_pk_bf16_f32 v3, v51, v27
	global_load_dwordx4 v[12:15], v[32:33], off offset:256
	v_add_f32_e32 v36, 0, v43
	v_add_f32_e32 v37, 0, v44
	v_add_f32_e32 v38, 0, v45
	v_add_f32_e32 v39, 0, v46
	v_add_f32_e32 v41, 0, v47
	v_add_f32_e32 v28, 0, v28
	v_add_f32_e32 v29, 0, v29
	s_waitcnt vmcnt(4)
	v_lshlrev_b32_e32 v42, 16, v20
	v_and_b32_e32 v20, 0xffff0000, v20
	v_lshlrev_b32_e32 v43, 16, v21
	v_and_b32_e32 v21, 0xffff0000, v21
	v_lshlrev_b32_e32 v44, 16, v22
	v_and_b32_e32 v22, 0xffff0000, v22
	v_lshlrev_b32_e32 v45, 16, v23
	v_and_b32_e32 v23, 0xffff0000, v23
	v_add_f32_e32 v20, v36, v20
	v_add_f32_e32 v36, v37, v43
	v_add_f32_e32 v21, v38, v21
	v_add_f32_e32 v37, v39, v44
	v_add_f32_e32 v22, v41, v22
	v_add_f32_e32 v28, v28, v45
	v_add_f32_e32 v23, v29, v23
	s_waitcnt vmcnt(3)
	v_lshlrev_b32_e32 v29, 16, v16
	v_and_b32_e32 v16, 0xffff0000, v16
	v_lshlrev_b32_e32 v38, 16, v17
	v_and_b32_e32 v17, 0xffff0000, v17
	v_lshlrev_b32_e32 v39, 16, v18
	v_and_b32_e32 v18, 0xffff0000, v18
	v_lshlrev_b32_e32 v41, 16, v19
	v_and_b32_e32 v19, 0xffff0000, v19
	v_add_f32_e32 v16, v20, v16
	v_add_f32_e32 v20, v36, v38
	v_add_f32_e32 v17, v21, v17
	v_add_f32_e32 v21, v37, v39
	v_add_f32_e32 v18, v22, v18
	v_add_f32_e32 v22, v28, v41
	v_add_f32_e32 v19, v23, v19
	s_waitcnt vmcnt(2)
	v_lshlrev_b32_e32 v36, 16, v10
	v_and_b32_e32 v10, 0xffff0000, v10
	v_lshlrev_b32_e32 v37, 16, v11
	v_and_b32_e32 v11, 0xffff0000, v11
	v_add_f32_e32 v10, v18, v10
	v_add_f32_e32 v18, v22, v37
	v_add_f32_e32 v11, v19, v11
	s_waitcnt vmcnt(1)
	v_lshlrev_b32_e32 v22, 16, v7
	v_and_b32_e32 v7, 0xffff0000, v7
	v_add_f32_e32 v7, v11, v7
	v_mul_f32_e32 v11, v24, v24
	v_fmac_f32_e32 v11, v48, v48
	v_add_f32_e32 v40, 0, v40
	v_fmac_f32_e32 v11, v49, v49
	v_add_f32_e32 v40, v40, v42
	v_fmac_f32_e32 v11, v25, v25
	v_add_f32_e32 v29, v40, v29
	v_lshlrev_b32_e32 v23, 16, v8
	v_and_b32_e32 v8, 0xffff0000, v8
	v_lshlrev_b32_e32 v28, 16, v9
	v_fmac_f32_e32 v11, v50, v50
	v_add_f32_e32 v23, v29, v23
	v_add_f32_e32 v8, v16, v8
	v_add_f32_e32 v16, v20, v28
	v_lshlrev_b32_e32 v19, 16, v4
	v_and_b32_e32 v4, 0xffff0000, v4
	v_lshlrev_b32_e32 v20, 16, v5
	v_fmac_f32_e32 v11, v26, v26
	v_and_b32_e32 v9, 0xffff0000, v9
	v_add_f32_e32 v19, v23, v19
	v_add_f32_e32 v4, v8, v4
	v_add_f32_e32 v8, v16, v20
	v_fmac_f32_e32 v11, v51, v51
	v_add_f32_e32 v9, v17, v9
	v_add_f32_e32 v17, v21, v36
	v_and_b32_e32 v5, 0xffff0000, v5
	v_lshlrev_b32_e32 v21, 16, v6
	v_fmac_f32_e32 v11, v27, v27
	v_add_f32_e32 v5, v9, v5
	v_add_f32_e32 v9, v17, v21
	v_and_b32_e32 v6, 0xffff0000, v6
	v_add_f32_e32 v6, v10, v6
	s_waitcnt vmcnt(0)
	v_lshlrev_b32_e32 v16, 16, v12
	v_and_b32_e32 v12, 0xffff0000, v12
	v_add_f32_e32 v19, v19, v108
	v_fmac_f32_e32 v16, s10, v19
	v_lshlrev_b32_e32 v17, 16, v13
	v_add_f32_e32 v4, v4, v109
	v_fmac_f32_e32 v12, s10, v4
	v_fmac_f32_e32 v11, v16, v16
	v_and_b32_e32 v13, 0xffff0000, v13
	v_add_f32_e32 v8, v8, v110
	v_fmac_f32_e32 v17, s10, v8
	v_fmac_f32_e32 v11, v12, v12
	v_add_f32_e32 v10, v18, v22
	v_lshlrev_b32_e32 v18, 16, v14
	v_add_f32_e32 v5, v5, v111
	v_fmac_f32_e32 v13, s10, v5
	v_fmac_f32_e32 v11, v17, v17
	v_and_b32_e32 v14, 0xffff0000, v14
	v_add_f32_e32 v9, v9, v112
	v_fmac_f32_e32 v18, s10, v9
	v_fmac_f32_e32 v11, v13, v13
	v_lshlrev_b32_e32 v20, 16, v15
	v_add_f32_e32 v6, v6, v113
	v_fmac_f32_e32 v14, s10, v6
	v_fmac_f32_e32 v11, v18, v18
	v_and_b32_e32 v15, 0xffff0000, v15
	v_add_f32_e32 v10, v10, v114
	v_fmac_f32_e32 v20, s10, v10
	v_fmac_f32_e32 v11, v14, v14
	v_add_f32_e32 v7, v7, v115
	v_fmac_f32_e32 v15, s10, v7
	v_fmac_f32_e32 v11, v20, v20
	v_fmac_f32_e32 v11, v15, v15
	ds_bpermute_b32 v4, v219, v11
	global_store_dwordx4 v[32:33], v[0:3], off
	s_nop 1
	v_cvt_pk_bf16_f32 v2, v16, v12
	s_waitcnt lgkmcnt(0)
	v_add_f32_e32 v0, v11, v4
	ds_bpermute_b32 v1, v218, v0
	v_cvt_pk_bf16_f32 v3, v17, v13
	v_cvt_pk_bf16_f32 v4, v18, v14
	v_cvt_pk_bf16_f32 v5, v20, v15
	global_store_dwordx4 v[32:33], v[2:5], off offset:256
	s_and_saveexec_b64 s[2:3], vcc
	s_cbranch_execz .LBB0_1418
	s_waitcnt lgkmcnt(0)
	v_add_f32_e32 v2, v0, v1
	s_lshl_b32 s4, s4, 2
	v_lshlrev_b64 v[0:1], 6, v[30:31]
	s_ashr_i32 s5, s4, 31
	v_lshl_add_u64 v[0:1], s[8:9], 0, v[0:1]
	v_lshl_add_u64 v[0:1], s[4:5], 2, v[0:1]
	v_lshlrev_b32_e32 v176, 2, v34
	v_lshl_add_u64 v[0:1], v[0:1], 0, v[176:177]
	global_store_dword v[0:1], v2, off

	.amdhsa_kernel _Z4mega6Params
		.amdhsa_group_segment_fixed_size 0
		.amdhsa_private_segment_fixed_size 0
		.amdhsa_kernarg_size 512
		.amdhsa_user_sgpr_count 2
		.amdhsa_user_sgpr_dispatch_ptr 0
		.amdhsa_user_sgpr_queue_ptr 0
		.amdhsa_user_sgpr_kernarg_segment_ptr 1
		.amdhsa_user_sgpr_dispatch_id 0
		.amdhsa_user_sgpr_kernarg_preload_length 0
		.amdhsa_user_sgpr_kernarg_preload_offset 0
		.amdhsa_user_sgpr_private_segment_size 0
		.amdhsa_uses_dynamic_stack 0
		.amdhsa_enable_private_segment 0
		.amdhsa_system_sgpr_workgroup_id_x 1
		.amdhsa_system_sgpr_workgroup_id_y 0
		.amdhsa_system_sgpr_workgroup_id_z 0
		.amdhsa_system_sgpr_workgroup_info 0
		.amdhsa_system_vgpr_workitem_id 0
		.amdhsa_next_free_vgpr 255
		.amdhsa_next_free_sgpr 100
		.amdhsa_accum_offset 256
		.amdhsa_reserve_vcc 1
		.amdhsa_float_round_mode_32 0
		.amdhsa_float_round_mode_16_64 0
		.amdhsa_float_denorm_mode_32 3
		.amdhsa_float_denorm_mode_16_64 3
		.amdhsa_dx10_clamp 1
		.amdhsa_ieee_mode 1
		.amdhsa_fp16_overflow 0
		.amdhsa_tg_split 0
		.amdhsa_exception_fp_ieee_invalid_op 0
		.amdhsa_exception_fp_denorm_src 0
		.amdhsa_exception_fp_ieee_div_zero 0
		.amdhsa_exception_fp_ieee_overflow 0
		.amdhsa_exception_fp_ieee_underflow 0
		.amdhsa_exception_fp_ieee_inexact 0
		.amdhsa_exception_int_div_zero 0
	.end_amdhsa_kernel

amdhsa.kernels:
  - .agpr_count:     0
    .args:
      - .offset:         0
        .size:           256
        .value_kind:     by_value
      - .offset:         256
        .size:           4
        .value_kind:     hidden_block_count_x
      - .offset:         260
        .size:           4
        .value_kind:     hidden_block_count_y
      - .offset:         264
        .size:           4
        .value_kind:     hidden_block_count_z
      - .offset:         268
        .size:           2
        .value_kind:     hidden_group_size_x
      - .offset:         270
        .size:           2
        .value_kind:     hidden_group_size_y
      - .offset:         272
        .size:           2
        .value_kind:     hidden_group_size_z
      - .offset:         274
        .size:           2
        .value_kind:     hidden_remainder_x
      - .offset:         276
        .size:           2
        .value_kind:     hidden_remainder_y
      - .offset:         278
        .size:           2
        .value_kind:     hidden_remainder_z
      - .offset:         296
        .size:           8
        .value_kind:     hidden_global_offset_x
      - .offset:         304
        .size:           8
        .value_kind:     hidden_global_offset_y
      - .offset:         312
        .size:           8
        .value_kind:     hidden_global_offset_z
      - .offset:         320
        .size:           2
        .value_kind:     hidden_grid_dims
      - .offset:         376
        .size:           4
        .value_kind:     hidden_dynamic_lds_size
    .group_segment_fixed_size: 0
    .kernarg_segment_align: 8
    .kernarg_segment_size: 512
    .language:       OpenCL C
    .language_version:
      - 2
      - 0
    .max_flat_workgroup_size: 512
    .name:           _Z4mega6Params
    .private_segment_fixed_size: 0
    .sgpr_count:     106
    .sgpr_spill_count: 6
    .symbol:         _Z4mega6Params.kd
    .uniform_work_group_size: 1
    .uses_dynamic_stack: false
    .vgpr_count:     255
    .vgpr_spill_count: 0
    .wavefront_size: 64
